# static priority waves 4-7 plus gemm3 VALU-free LDS-DMA issue (SALU m0, saddr global_load_lds)
# speedup vs baseline: 1.0106x; 1.0106x over previous
; template <int BMODE, class Epi, class TileFn>
; DEV void gemm_loop(LAS unsigned char* lds, const bf16_t* __restrict__ A, int lda, const bf16_t* __restrict__ B, int ldb, int K, const Epi& epi, int t0, int tstep, int tend, const TileFn& tf) {
;     ...
;         int nrow = brow, ncol = bcol;
;         if (has_next) tf(tt + tstep, nrow, ncol);
;         const char* nA = (const char*)(A + (size_t)nrow * lda);
;         const char* nB = BMODE == 0 ? (const char*)(B + (size_t)ncol * ldb) : (const char*)(B + (size_t)ncol * 8);
;         for (int t = 0; t < nt; t += 2) {
.LBB0_440:
	s_ashr_i32 s53, s52, 31
	s_lshl_b64 s[76:77], s[52:53], 11
	s_add_u32 s29, s72, s76
	s_addc_u32 s30, s73, s77
	s_ashr_i32 s55, s54, 31
	s_lshl_b64 s[80:81], s[54:55], 11
	s_add_u32 s50, s46, s80
	s_addc_u32 s53, s47, s81
	s_add_u32 s55, s66, s36
	s_addc_u32 s74, s67, s37
	v_readlane_b32 s31, v254, 51
	s_add_u32 s75, s31, s8
	v_readlane_b32 s8, v254, 52
	v_lshl_add_u64 v[140:141], v[136:137], 0, s[36:37]
	v_lshl_add_u64 v[142:143], v[138:139], 0, s[36:37]
	s_addc_u32 s83, s8, s9
	s_mov_b32 s92, -2
	s_mov_b64 s[36:37], 0
	v_readfirstlane_b32 s101, v188
	s_nop 3
	s_cmp_lt_u32 s101, 0x100
	s_cbranch_scc1 .Lsp_441
	s_setprio 1

; template <int BMODE, class Epi, class TileFn>
; DEV void gemm_loop(LAS unsigned char* lds, const bf16_t* __restrict__ A, int lda, const bf16_t* __restrict__ B, int ldb, int K, const Epi& epi, int t0, int tstep, int tend, const TileFn& tf) {
;     ...
;         int nrow = brow, ncol = bcol;
;         if (has_next) tf(tt + tstep, nrow, ncol);
;         const char* nA = (const char*)(A + (size_t)nrow * lda);
;         const char* nB = BMODE == 0 ? (const char*)(B + (size_t)ncol * ldb) : (const char*)(B + (size_t)ncol * 8);
;         for (int t = 0; t < nt; t += 2) {
.LBB0_1238:
	s_ashr_i32 s49, s48, 31
	s_lshl_b64 s[54:55], s[48:49], 11
	s_add_u32 s28, s88, s54
	s_addc_u32 s29, s89, s55
	s_ashr_i32 s53, s52, 31
	s_lshl_b64 s[74:75], s[52:53], 11
	s_add_u32 s30, s38, s74
	s_addc_u32 s37, s39, s75
	s_add_u32 s49, s66, s8
	s_addc_u32 s50, s67, s9
	v_lshl_add_u64 v[120:121], v[200:201], 0, s[8:9]
	v_lshl_add_u64 v[122:123], v[202:203], 0, s[8:9]
	v_readlane_b32 s8, v254, 61
	s_add_u32 s53, s8, s0
	v_readlane_b32 s0, v254, 62
	s_addc_u32 s80, s0, s1
	s_mov_b32 s81, -2
	s_mov_b64 s[0:1], 0
	v_readfirstlane_b32 s101, v188
	s_nop 3
	s_cmp_lt_u32 s101, 0x100
	s_cbranch_scc1 .Lsp_1239
	s_setprio 1

; #define WAIT_V(n) asm volatile("s_waitcnt vmcnt(" #n ")" ::: "memory")
; #define WAIT_L(n) asm volatile("s_waitcnt lgkmcnt(" #n ")" ::: "memory")
; #define BAR __builtin_amdgcn_s_barrier()
; #define SCHED __builtin_amdgcn_sched_barrier(0)
; #define STG_A(b, h, ptr) do { const char* _g = (ptr) + (h) * ahalf; LAS unsigned char* _l = lw + ((b) * 2 + (h)) * 16384; GLDS(_g + voa0, _l); GLDS(_g + voa1, _l + 8192); } while (0)
; #define STG_B(b, h, ptr) do { const char* _g = (ptr) + (h) * bhalf; LAS unsigned char* _l = lw + 65536 + ((b) * 2 + (h)) * 16384; GLDS(_g + vob0, _l); GLDS(_g + vob1, _l + 8192); } while (0)
; #define LDA(dst, b, h) _Pragma("unroll") for (int m = 0; m < 4; ++m) _Pragma("unroll") for (int k = 0; k < 2; ++k) dst[m][k] = *(const LAS bf16x8*)(la + ((b) * 2 + (h)) * 16384 + m * 2048 + k * 1024)
; #define LDB(dst, b, h) _Pragma("unroll") for (int n = 0; n < 2; ++n) _Pragma("unroll") for (int k = 0; k < 2; ++k) dst[n][k] = *(const LAS bf16x8*)(lb + ((b) * 2 + (h)) * 16384 + n * 2048 + k * 1024)
; template <int BMODE, class Epi, class TileFn>
; DEV void gemm_loop(LAS unsigned char* lds, const bf16_t* __restrict__ A, int lda, const bf16_t* __restrict__ B, int ldb, int K, const Epi& epi, int t0, int tstep, int tend, const TileFn& tf) {
;     ...
;         int nrow = brow, ncol = bcol;
;         if (has_next) tf(tt + tstep, nrow, ncol);
;         const char* nA = (const char*)(A + (size_t)nrow * lda);
;         const char* nB = BMODE == 0 ? (const char*)(B + (size_t)ncol * ldb) : (const char*)(B + (size_t)ncol * 8);
;         for (int t = 0; t < nt; t += 2) {
;             const bool last = (t == nt - 2);
;             const char* a1 = cA + (size_t)(t + 1) * 128;
;             const char* a2 = last ? nA : cA + (size_t)(t + 2) * 128;
;             const char* b2 = last ? nB : cB + (size_t)(t + 2) * bks;
;             const char* a3 = a2 + 128; const char* b3 = b2 + bks;
;             LDB(B0, 0, 0); LDB(B1, 0, 1); SCHED; LDA(At, 0, 0); STG_A(1, 1, a1);
;             WAIT_V(8); WAIT_L(0); BAR; MMA(0, 0, At, B0); MMA(0, 1, At, B1); BAR; SCHED;
;             LDA(At, 0, 1); STG_B(0, 0, b2); STG_B(0, 1, b2); STG_A(0, 0, a2);
;             WAIT_V(8); WAIT_L(0); BAR; MMA(1, 0, At, B0); MMA(1, 1, At, B1); BAR; SCHED;
.LBB0_1337:
	v_readfirstlane_b32 s100, v141
	s_ashr_i32 s53, s52, 31
	s_lshl_b64 s[82:83], s[52:53], 11
	s_add_u32 s30, s72, s82
	s_addc_u32 s50, s73, s83
	s_ashr_i32 s81, s80, 31
	s_lshl_b64 s[40:41], s[80:81], 11
	s_add_u32 s53, s48, s40
	s_addc_u32 s74, s49, s41
	s_add_u32 s75, s66, s36
	s_addc_u32 s81, s67, s37
	v_readlane_b32 s31, v254, 63
	s_add_u32 s92, s31, s8
	v_readlane_b32 s8, v250, 0
	v_lshl_add_u64 v[136:137], v[132:133], 0, s[36:37]
	v_lshl_add_u64 v[138:139], v[134:135], 0, s[36:37]
	s_addc_u32 s93, s8, s9
	s_mov_b32 s94, -2
	s_mov_b64 s[36:37], 0
	v_readfirstlane_b32 s101, v188
	s_nop 3
	s_cmp_lt_u32 s101, 0x100
	s_cbranch_scc1 .Lsp_1338
	s_setprio 1
.Lsp_1338:
	ds_read_b128 v[158:161], v156
	ds_read_b128 v[162:165], v156 offset:1024
	ds_read_b128 v[166:169], v156 offset:2048
	ds_read_b128 v[170:173], v156 offset:3072
	ds_read_b128 v[174:177], v156 offset:16384
	ds_read_b128 v[178:181], v156 offset:17408
	ds_read_b128 v[182:185], v156 offset:18432
	ds_read_b128 v[196:199], v156 offset:19456
	s_add_u32 s8, s75, s36
	s_addc_u32 s9, s81, s37
	s_add_u32 s8, s8, 0x62e6100
	s_addc_u32 s9, s9, 0
	s_add_u32 s31, s92, s36
	s_addc_u32 s95, s93, s37
	s_cmpk_eq_i32 s36, 0x700
	s_cselect_b32 s55, s50, s9
	s_cselect_b32 s54, s30, s8
	s_cselect_b32 s9, s74, s95
	s_cselect_b32 s8, s53, s31
	v_lshl_add_u64 v[186:187], v[136:137], 0, s[36:37]
	v_lshl_add_u64 v[204:205], v[138:139], 0, s[36:37]
	s_add_u32 m0, s100, 0xc000
	ds_read_b128 v[200:203], v157
	ds_read_b128 v[212:215], v157 offset:1024
	ds_read_b128 v[216:219], v157 offset:2048
	ds_read_b128 v[220:223], v157 offset:3072
	ds_read_b128 v[224:227], v157 offset:4096
	ds_read_b128 v[228:231], v157 offset:5120
	ds_read_b128 v[232:235], v157 offset:6144
	ds_read_b128 v[236:239], v157 offset:7168
	global_load_lds_dwordx4 v[186:187], off
	s_add_u32 m0, s100, 0xe000
	s_nop 0
	global_load_lds_dwordx4 v[204:205], off
	s_waitcnt vmcnt(8)
	s_waitcnt lgkmcnt(0)
	s_barrier
	s_waitcnt lgkmcnt(0)
	v_mfma_f32_16x16x32_bf16 v[124:127], v[158:161], v[200:203], 0
	v_mfma_f32_16x16x32_bf16 v[120:123], v[166:169], v[200:203], 0
	v_mfma_f32_16x16x32_bf16 v[104:107], v[158:161], v[216:219], 0
	v_mfma_f32_16x16x32_bf16 v[108:111], v[166:169], v[216:219], 0
	v_mfma_f32_16x16x32_bf16 v[92:95], v[158:161], v[224:227], 0
	v_mfma_f32_16x16x32_bf16 v[88:91], v[166:169], v[224:227], 0
	v_mfma_f32_16x16x32_bf16 v[72:75], v[158:161], v[232:235], 0
	v_mfma_f32_16x16x32_bf16 v[76:79], v[166:169], v[232:235], 0
	v_mfma_f32_16x16x32_bf16 v[124:127], v[162:165], v[212:215], v[124:127]
	v_mfma_f32_16x16x32_bf16 v[120:123], v[170:173], v[212:215], v[120:123]
	v_mfma_f32_16x16x32_bf16 v[104:107], v[162:165], v[220:223], v[104:107]
	v_mfma_f32_16x16x32_bf16 v[108:111], v[170:173], v[220:223], v[108:111]
	v_mfma_f32_16x16x32_bf16 v[92:95], v[162:165], v[228:231], v[92:95]
	v_mfma_f32_16x16x32_bf16 v[88:91], v[170:173], v[228:231], v[88:91]
	v_mfma_f32_16x16x32_bf16 v[72:75], v[162:165], v[236:239], v[72:75]
	v_mfma_f32_16x16x32_bf16 v[76:79], v[170:173], v[236:239], v[76:79]
	v_mfma_f32_16x16x32_bf16 v[116:119], v[174:177], v[200:203], 0
	v_mfma_f32_16x16x32_bf16 v[112:115], v[182:185], v[200:203], 0
	v_mfma_f32_16x16x32_bf16 v[96:99], v[174:177], v[216:219], 0
	v_mfma_f32_16x16x32_bf16 v[100:103], v[182:185], v[216:219], 0
	v_mfma_f32_16x16x32_bf16 v[84:87], v[174:177], v[224:227], 0
	v_mfma_f32_16x16x32_bf16 v[80:83], v[182:185], v[224:227], 0
	v_mfma_f32_16x16x32_bf16 v[64:67], v[174:177], v[232:235], 0
	v_mfma_f32_16x16x32_bf16 v[68:71], v[182:185], v[232:235], 0
	v_mfma_f32_16x16x32_bf16 v[116:119], v[178:181], v[212:215], v[116:119]
	v_mfma_f32_16x16x32_bf16 v[112:115], v[196:199], v[212:215], v[112:115]
	v_mfma_f32_16x16x32_bf16 v[96:99], v[178:181], v[220:223], v[96:99]
	v_mfma_f32_16x16x32_bf16 v[100:103], v[196:199], v[220:223], v[100:103]
	v_mfma_f32_16x16x32_bf16 v[84:87], v[178:181], v[228:231], v[84:87]
	v_mfma_f32_16x16x32_bf16 v[80:83], v[196:199], v[228:231], v[80:83]
	v_mfma_f32_16x16x32_bf16 v[64:67], v[178:181], v[236:239], v[64:67]
	v_mfma_f32_16x16x32_bf16 v[68:71], v[196:199], v[236:239], v[68:71]
	s_barrier
	ds_read_b128 v[200:203], v157 offset:16384
	ds_read_b128 v[212:215], v157 offset:17408
	ds_read_b128 v[216:219], v157 offset:18432
	ds_read_b128 v[220:223], v157 offset:19456
	ds_read_b128 v[224:227], v157 offset:20480
	ds_read_b128 v[228:231], v157 offset:21504
	ds_read_b128 v[232:235], v157 offset:22528
	ds_read_b128 v[236:239], v157 offset:23552
	s_add_u32 s96, s8, 0x40000
	s_addc_u32 s97, s9, 0
	s_add_u32 m0, s100, 0x10000
	s_nop 0
	global_load_lds_dwordx4 v128, s[8:9]
	s_add_u32 m0, s100, 0x12000
	s_nop 0
	global_load_lds_dwordx4 v130, s[8:9]
	s_add_u32 m0, s100, 0x14000
	s_nop 0
	global_load_lds_dwordx4 v128, s[96:97]
	s_add_u32 m0, s100, 0x16000
	s_nop 0
	global_load_lds_dwordx4 v130, s[96:97]
	s_mov_b32 m0, s100
	s_nop 0
	global_load_lds_dwordx4 v128, s[54:55]
	s_add_u32 m0, s100, 0x2000
	s_nop 0
	global_load_lds_dwordx4 v130, s[54:55]
	s_waitcnt vmcnt(8)
	s_waitcnt lgkmcnt(0)
	s_barrier
; #define WAIT_V(n) asm volatile("s_waitcnt vmcnt(" #n ")" ::: "memory")
; #define WAIT_L(n) asm volatile("s_waitcnt lgkmcnt(" #n ")" ::: "memory")
; #define BAR __builtin_amdgcn_s_barrier()
; #define SCHED __builtin_amdgcn_sched_barrier(0)
; #define STG_A(b, h, ptr) do { const char* _g = (ptr) + (h) * ahalf; LAS unsigned char* _l = lw + ((b) * 2 + (h)) * 16384; GLDS(_g + voa0, _l); GLDS(_g + voa1, _l + 8192); } while (0)
; #define STG_B(b, h, ptr) do { const char* _g = (ptr) + (h) * bhalf; LAS unsigned char* _l = lw + 65536 + ((b) * 2 + (h)) * 16384; GLDS(_g + vob0, _l); GLDS(_g + vob1, _l + 8192); } while (0)
; #define LDA(dst, b, h) _Pragma("unroll") for (int m = 0; m < 4; ++m) _Pragma("unroll") for (int k = 0; k < 2; ++k) dst[m][k] = *(const LAS bf16x8*)(la + ((b) * 2 + (h)) * 16384 + m * 2048 + k * 1024)
; #define LDB(dst, b, h) _Pragma("unroll") for (int n = 0; n < 2; ++n) _Pragma("unroll") for (int k = 0; k < 2; ++k) dst[n][k] = *(const LAS bf16x8*)(lb + ((b) * 2 + (h)) * 16384 + n * 2048 + k * 1024)
; #define MMA(ai, bj, Af, Bf) do { __builtin_amdgcn_s_setprio(1); \
;     _Pragma("unroll") for (int m = 0; m < 4; ++m) _Pragma("unroll") for (int n = 0; n < 2; ++n) _Pragma("unroll") for (int k = 0; k < 2; ++k) \
;         acc[ai][bj][m][n] = __builtin_amdgcn_mfma_f32_16x16x32_bf16(Bf[n][k], Af[m][k], acc[ai][bj][m][n], 0, 0, 0); \
;     __builtin_amdgcn_s_setprio(0); } while (0)
; template <int BMODE, class Epi, class TileFn>
; DEV void gemm_loop(LAS unsigned char* lds, const bf16_t* __restrict__ A, int lda, const bf16_t* __restrict__ B, int ldb, int K, const Epi& epi, int t0, int tstep, int tend, const TileFn& tf) {
;     ...
;         for (int t = 0; t < nt; t += 2) {
;             const bool last = (t == nt - 2);
;             const char* a1 = cA + (size_t)(t + 1) * 128;
;             const char* a2 = last ? nA : cA + (size_t)(t + 2) * 128;
;             const char* b2 = last ? nB : cB + (size_t)(t + 2) * bks;
;             const char* a3 = a2 + 128; const char* b3 = b2 + bks;
;             LDB(B0, 0, 0); LDB(B1, 0, 1); SCHED; LDA(At, 0, 0); STG_A(1, 1, a1);
;             WAIT_V(8); WAIT_L(0); BAR; MMA(0, 0, At, B0); MMA(0, 1, At, B1); BAR; SCHED;
;             LDA(At, 0, 1); STG_B(0, 0, b2); STG_B(0, 1, b2); STG_A(0, 0, a2);
;             WAIT_V(8); WAIT_L(0); BAR; MMA(1, 0, At, B0); MMA(1, 1, At, B1); BAR; SCHED;
	s_waitcnt lgkmcnt(0)
	v_mfma_f32_16x16x32_bf16 v[60:63], v[158:161], v[200:203], 0
	v_mfma_f32_16x16x32_bf16 v[56:59], v[166:169], v[200:203], 0
	v_mfma_f32_16x16x32_bf16 v[40:43], v[158:161], v[216:219], 0
	v_mfma_f32_16x16x32_bf16 v[44:47], v[166:169], v[216:219], 0
	v_mfma_f32_16x16x32_bf16 v[28:31], v[158:161], v[224:227], 0
	v_mfma_f32_16x16x32_bf16 v[24:27], v[166:169], v[224:227], 0
	v_mfma_f32_16x16x32_bf16 v[8:11], v[158:161], v[232:235], 0
	v_mfma_f32_16x16x32_bf16 v[12:15], v[166:169], v[232:235], 0
	v_mfma_f32_16x16x32_bf16 v[60:63], v[162:165], v[212:215], v[60:63]
	v_mfma_f32_16x16x32_bf16 v[56:59], v[170:173], v[212:215], v[56:59]
	v_mfma_f32_16x16x32_bf16 v[40:43], v[162:165], v[220:223], v[40:43]
	v_mfma_f32_16x16x32_bf16 v[44:47], v[170:173], v[220:223], v[44:47]
	v_mfma_f32_16x16x32_bf16 v[28:31], v[162:165], v[228:231], v[28:31]
	v_mfma_f32_16x16x32_bf16 v[24:27], v[170:173], v[228:231], v[24:27]
	v_mfma_f32_16x16x32_bf16 v[8:11], v[162:165], v[236:239], v[8:11]
	v_mfma_f32_16x16x32_bf16 v[12:15], v[170:173], v[236:239], v[12:15]
	v_mfma_f32_16x16x32_bf16 v[52:55], v[174:177], v[200:203], 0
	v_mfma_f32_16x16x32_bf16 v[48:51], v[182:185], v[200:203], 0
	v_mfma_f32_16x16x32_bf16 v[32:35], v[174:177], v[216:219], 0
	v_mfma_f32_16x16x32_bf16 v[36:39], v[182:185], v[216:219], 0
	v_mfma_f32_16x16x32_bf16 v[20:23], v[174:177], v[224:227], 0
	v_mfma_f32_16x16x32_bf16 v[16:19], v[182:185], v[224:227], 0
	v_mfma_f32_16x16x32_bf16 v[0:3], v[174:177], v[232:235], 0
	v_mfma_f32_16x16x32_bf16 v[4:7], v[182:185], v[232:235], 0
	v_mfma_f32_16x16x32_bf16 v[52:55], v[178:181], v[212:215], v[52:55]
	v_mfma_f32_16x16x32_bf16 v[48:51], v[196:199], v[212:215], v[48:51]
	v_mfma_f32_16x16x32_bf16 v[32:35], v[178:181], v[220:223], v[32:35]
	v_mfma_f32_16x16x32_bf16 v[36:39], v[196:199], v[220:223], v[36:39]
	v_mfma_f32_16x16x32_bf16 v[20:23], v[178:181], v[228:231], v[20:23]
	v_mfma_f32_16x16x32_bf16 v[16:19], v[196:199], v[228:231], v[16:19]
	v_mfma_f32_16x16x32_bf16 v[0:3], v[178:181], v[236:239], v[0:3]
	v_mfma_f32_16x16x32_bf16 v[4:7], v[196:199], v[236:239], v[4:7]
	s_barrier
	s_branch .Lkmid_1338
.LBB0_1338:
	ds_read_b128 v[158:161], v156
	ds_read_b128 v[162:165], v156 offset:1024
	ds_read_b128 v[166:169], v156 offset:2048
	ds_read_b128 v[170:173], v156 offset:3072
	ds_read_b128 v[174:177], v156 offset:16384
	ds_read_b128 v[178:181], v156 offset:17408
	ds_read_b128 v[182:185], v156 offset:18432
	ds_read_b128 v[196:199], v156 offset:19456
	s_add_u32 s8, s75, s36
	s_addc_u32 s9, s81, s37
	s_add_u32 s8, s8, 0x62e6100
	s_addc_u32 s9, s9, 0
	s_add_u32 s31, s92, s36
	s_addc_u32 s95, s93, s37
	s_cmpk_eq_i32 s36, 0x700
	s_cselect_b32 s55, s50, s9
	s_cselect_b32 s54, s30, s8
	s_cselect_b32 s9, s74, s95
	s_cselect_b32 s8, s53, s31
	v_lshl_add_u64 v[186:187], v[136:137], 0, s[36:37]
	v_lshl_add_u64 v[204:205], v[138:139], 0, s[36:37]
	s_add_u32 m0, s100, 0xc000
	ds_read_b128 v[200:203], v157
	ds_read_b128 v[212:215], v157 offset:1024
	ds_read_b128 v[216:219], v157 offset:2048
	ds_read_b128 v[220:223], v157 offset:3072
	ds_read_b128 v[224:227], v157 offset:4096
	ds_read_b128 v[228:231], v157 offset:5120
	ds_read_b128 v[232:235], v157 offset:6144
	ds_read_b128 v[236:239], v157 offset:7168
	global_load_lds_dwordx4 v[186:187], off
	s_add_u32 m0, s100, 0xe000
	s_nop 0
	global_load_lds_dwordx4 v[204:205], off
	s_waitcnt vmcnt(8)
	s_waitcnt lgkmcnt(0)
	s_barrier
	s_waitcnt lgkmcnt(0)
	v_mfma_f32_16x16x32_bf16 v[124:127], v[158:161], v[200:203], v[124:127]
	v_mfma_f32_16x16x32_bf16 v[120:123], v[166:169], v[200:203], v[120:123]
	v_mfma_f32_16x16x32_bf16 v[104:107], v[158:161], v[216:219], v[104:107]
	v_mfma_f32_16x16x32_bf16 v[108:111], v[166:169], v[216:219], v[108:111]
	v_mfma_f32_16x16x32_bf16 v[92:95], v[158:161], v[224:227], v[92:95]
	v_mfma_f32_16x16x32_bf16 v[88:91], v[166:169], v[224:227], v[88:91]
	v_mfma_f32_16x16x32_bf16 v[72:75], v[158:161], v[232:235], v[72:75]
	v_mfma_f32_16x16x32_bf16 v[76:79], v[166:169], v[232:235], v[76:79]
	v_mfma_f32_16x16x32_bf16 v[124:127], v[162:165], v[212:215], v[124:127]
	v_mfma_f32_16x16x32_bf16 v[120:123], v[170:173], v[212:215], v[120:123]
	v_mfma_f32_16x16x32_bf16 v[104:107], v[162:165], v[220:223], v[104:107]
	v_mfma_f32_16x16x32_bf16 v[108:111], v[170:173], v[220:223], v[108:111]
	v_mfma_f32_16x16x32_bf16 v[92:95], v[162:165], v[228:231], v[92:95]
	v_mfma_f32_16x16x32_bf16 v[88:91], v[170:173], v[228:231], v[88:91]
	v_mfma_f32_16x16x32_bf16 v[72:75], v[162:165], v[236:239], v[72:75]
	v_mfma_f32_16x16x32_bf16 v[76:79], v[170:173], v[236:239], v[76:79]
	v_mfma_f32_16x16x32_bf16 v[116:119], v[174:177], v[200:203], v[116:119]
	v_mfma_f32_16x16x32_bf16 v[112:115], v[182:185], v[200:203], v[112:115]
	v_mfma_f32_16x16x32_bf16 v[96:99], v[174:177], v[216:219], v[96:99]
	v_mfma_f32_16x16x32_bf16 v[100:103], v[182:185], v[216:219], v[100:103]
	v_mfma_f32_16x16x32_bf16 v[84:87], v[174:177], v[224:227], v[84:87]
	v_mfma_f32_16x16x32_bf16 v[80:83], v[182:185], v[224:227], v[80:83]
	v_mfma_f32_16x16x32_bf16 v[64:67], v[174:177], v[232:235], v[64:67]
	v_mfma_f32_16x16x32_bf16 v[68:71], v[182:185], v[232:235], v[68:71]
	v_mfma_f32_16x16x32_bf16 v[116:119], v[178:181], v[212:215], v[116:119]
	v_mfma_f32_16x16x32_bf16 v[112:115], v[196:199], v[212:215], v[112:115]
	v_mfma_f32_16x16x32_bf16 v[96:99], v[178:181], v[220:223], v[96:99]
	v_mfma_f32_16x16x32_bf16 v[100:103], v[196:199], v[220:223], v[100:103]
	v_mfma_f32_16x16x32_bf16 v[84:87], v[178:181], v[228:231], v[84:87]
	v_mfma_f32_16x16x32_bf16 v[80:83], v[196:199], v[228:231], v[80:83]
	v_mfma_f32_16x16x32_bf16 v[64:67], v[178:181], v[236:239], v[64:67]
	v_mfma_f32_16x16x32_bf16 v[68:71], v[196:199], v[236:239], v[68:71]
	s_barrier
; #define WAIT_V(n) asm volatile("s_waitcnt vmcnt(" #n ")" ::: "memory")
; #define WAIT_L(n) asm volatile("s_waitcnt lgkmcnt(" #n ")" ::: "memory")
; #define BAR __builtin_amdgcn_s_barrier()
; #define SCHED __builtin_amdgcn_sched_barrier(0)
; #define STG_A(b, h, ptr) do { const char* _g = (ptr) + (h) * ahalf; LAS unsigned char* _l = lw + ((b) * 2 + (h)) * 16384; GLDS(_g + voa0, _l); GLDS(_g + voa1, _l + 8192); } while (0)
; #define STG_B(b, h, ptr) do { const char* _g = (ptr) + (h) * bhalf; LAS unsigned char* _l = lw + 65536 + ((b) * 2 + (h)) * 16384; GLDS(_g + vob0, _l); GLDS(_g + vob1, _l + 8192); } while (0)
; #define LDA(dst, b, h) _Pragma("unroll") for (int m = 0; m < 4; ++m) _Pragma("unroll") for (int k = 0; k < 2; ++k) dst[m][k] = *(const LAS bf16x8*)(la + ((b) * 2 + (h)) * 16384 + m * 2048 + k * 1024)
; #define MMA(ai, bj, Af, Bf) do { __builtin_amdgcn_s_setprio(1); \
;     _Pragma("unroll") for (int m = 0; m < 4; ++m) _Pragma("unroll") for (int n = 0; n < 2; ++n) _Pragma("unroll") for (int k = 0; k < 2; ++k) \
;         acc[ai][bj][m][n] = __builtin_amdgcn_mfma_f32_16x16x32_bf16(Bf[n][k], Af[m][k], acc[ai][bj][m][n], 0, 0, 0); \
;     __builtin_amdgcn_s_setprio(0); } while (0)
; template <int BMODE, class Epi, class TileFn>
; DEV void gemm_loop(LAS unsigned char* lds, const bf16_t* __restrict__ A, int lda, const bf16_t* __restrict__ B, int ldb, int K, const Epi& epi, int t0, int tstep, int tend, const TileFn& tf) {
;     ...
;             LDA(At, 0, 1); STG_B(0, 0, b2); STG_B(0, 1, b2); STG_A(0, 0, a2);
;             WAIT_V(8); WAIT_L(0); BAR; MMA(1, 0, At, B0); MMA(1, 1, At, B1); BAR; SCHED;
	ds_read_b128 v[200:203], v157 offset:16384
	ds_read_b128 v[212:215], v157 offset:17408
	ds_read_b128 v[216:219], v157 offset:18432
	ds_read_b128 v[220:223], v157 offset:19456
	ds_read_b128 v[224:227], v157 offset:20480
	ds_read_b128 v[228:231], v157 offset:21504
	ds_read_b128 v[232:235], v157 offset:22528
	ds_read_b128 v[236:239], v157 offset:23552
	s_add_u32 s96, s8, 0x40000
	s_addc_u32 s97, s9, 0
	s_add_u32 m0, s100, 0x10000
	s_nop 0
	global_load_lds_dwordx4 v128, s[8:9]
	s_add_u32 m0, s100, 0x12000
	s_nop 0
	global_load_lds_dwordx4 v130, s[8:9]
	s_add_u32 m0, s100, 0x14000
	s_nop 0
	global_load_lds_dwordx4 v128, s[96:97]
	s_add_u32 m0, s100, 0x16000
	s_nop 0
	global_load_lds_dwordx4 v130, s[96:97]
	s_mov_b32 m0, s100
	s_nop 0
	global_load_lds_dwordx4 v128, s[54:55]
	s_add_u32 m0, s100, 0x2000
	s_nop 0
	global_load_lds_dwordx4 v130, s[54:55]
	s_waitcnt vmcnt(8)
	s_waitcnt lgkmcnt(0)
	s_barrier
	s_waitcnt lgkmcnt(0)
	v_mfma_f32_16x16x32_bf16 v[60:63], v[158:161], v[200:203], v[60:63]
	v_mfma_f32_16x16x32_bf16 v[56:59], v[166:169], v[200:203], v[56:59]
	v_mfma_f32_16x16x32_bf16 v[40:43], v[158:161], v[216:219], v[40:43]
	v_mfma_f32_16x16x32_bf16 v[44:47], v[166:169], v[216:219], v[44:47]
	v_mfma_f32_16x16x32_bf16 v[28:31], v[158:161], v[224:227], v[28:31]
	v_mfma_f32_16x16x32_bf16 v[24:27], v[166:169], v[224:227], v[24:27]
	v_mfma_f32_16x16x32_bf16 v[8:11], v[158:161], v[232:235], v[8:11]
	v_mfma_f32_16x16x32_bf16 v[12:15], v[166:169], v[232:235], v[12:15]
	v_mfma_f32_16x16x32_bf16 v[60:63], v[162:165], v[212:215], v[60:63]
	v_mfma_f32_16x16x32_bf16 v[56:59], v[170:173], v[212:215], v[56:59]
	v_mfma_f32_16x16x32_bf16 v[40:43], v[162:165], v[220:223], v[40:43]
	v_mfma_f32_16x16x32_bf16 v[44:47], v[170:173], v[220:223], v[44:47]
	v_mfma_f32_16x16x32_bf16 v[28:31], v[162:165], v[228:231], v[28:31]
	v_mfma_f32_16x16x32_bf16 v[24:27], v[170:173], v[228:231], v[24:27]
	v_mfma_f32_16x16x32_bf16 v[8:11], v[162:165], v[236:239], v[8:11]
	v_mfma_f32_16x16x32_bf16 v[12:15], v[170:173], v[236:239], v[12:15]
	v_mfma_f32_16x16x32_bf16 v[52:55], v[174:177], v[200:203], v[52:55]
	v_mfma_f32_16x16x32_bf16 v[48:51], v[182:185], v[200:203], v[48:51]
	v_mfma_f32_16x16x32_bf16 v[32:35], v[174:177], v[216:219], v[32:35]
	v_mfma_f32_16x16x32_bf16 v[36:39], v[182:185], v[216:219], v[36:39]
	v_mfma_f32_16x16x32_bf16 v[20:23], v[174:177], v[224:227], v[20:23]
	v_mfma_f32_16x16x32_bf16 v[16:19], v[182:185], v[224:227], v[16:19]
	v_mfma_f32_16x16x32_bf16 v[0:3], v[174:177], v[232:235], v[0:3]
	v_mfma_f32_16x16x32_bf16 v[4:7], v[182:185], v[232:235], v[4:7]
	v_mfma_f32_16x16x32_bf16 v[52:55], v[178:181], v[212:215], v[52:55]
	v_mfma_f32_16x16x32_bf16 v[48:51], v[196:199], v[212:215], v[48:51]
	v_mfma_f32_16x16x32_bf16 v[32:35], v[178:181], v[220:223], v[32:35]
	v_mfma_f32_16x16x32_bf16 v[36:39], v[196:199], v[220:223], v[36:39]
	v_mfma_f32_16x16x32_bf16 v[20:23], v[178:181], v[228:231], v[20:23]
	v_mfma_f32_16x16x32_bf16 v[16:19], v[196:199], v[228:231], v[16:19]
	v_mfma_f32_16x16x32_bf16 v[0:3], v[178:181], v[236:239], v[0:3]
	v_mfma_f32_16x16x32_bf16 v[4:7], v[196:199], v[236:239], v[4:7]
	s_barrier
; #define WAIT_V(n) asm volatile("s_waitcnt vmcnt(" #n ")" ::: "memory")
; #define WAIT_L(n) asm volatile("s_waitcnt lgkmcnt(" #n ")" ::: "memory")
; #define BAR __builtin_amdgcn_s_barrier()
; #define SCHED __builtin_amdgcn_sched_barrier(0)
; #define STG_A(b, h, ptr) do { const char* _g = (ptr) + (h) * ahalf; LAS unsigned char* _l = lw + ((b) * 2 + (h)) * 16384; GLDS(_g + voa0, _l); GLDS(_g + voa1, _l + 8192); } while (0)
; #define STG_B(b, h, ptr) do { const char* _g = (ptr) + (h) * bhalf; LAS unsigned char* _l = lw + 65536 + ((b) * 2 + (h)) * 16384; GLDS(_g + vob0, _l); GLDS(_g + vob1, _l + 8192); } while (0)
; #define LDA(dst, b, h) _Pragma("unroll") for (int m = 0; m < 4; ++m) _Pragma("unroll") for (int k = 0; k < 2; ++k) dst[m][k] = *(const LAS bf16x8*)(la + ((b) * 2 + (h)) * 16384 + m * 2048 + k * 1024)
; #define LDB(dst, b, h) _Pragma("unroll") for (int n = 0; n < 2; ++n) _Pragma("unroll") for (int k = 0; k < 2; ++k) dst[n][k] = *(const LAS bf16x8*)(lb + ((b) * 2 + (h)) * 16384 + n * 2048 + k * 1024)
; #define MMA(ai, bj, Af, Bf) do { __builtin_amdgcn_s_setprio(1); \
;     _Pragma("unroll") for (int m = 0; m < 4; ++m) _Pragma("unroll") for (int n = 0; n < 2; ++n) _Pragma("unroll") for (int k = 0; k < 2; ++k) \
;         acc[ai][bj][m][n] = __builtin_amdgcn_mfma_f32_16x16x32_bf16(Bf[n][k], Af[m][k], acc[ai][bj][m][n], 0, 0, 0); \
;     __builtin_amdgcn_s_setprio(0); } while (0)
; template <int BMODE, class Epi, class TileFn>
; DEV void gemm_loop(LAS unsigned char* lds, const bf16_t* __restrict__ A, int lda, const bf16_t* __restrict__ B, int ldb, int K, const Epi& epi, int t0, int tstep, int tend, const TileFn& tf) {
;     ...
;             LDB(B0, 1, 0); LDB(B1, 1, 1); SCHED; LDA(At, 1, 0); STG_A(0, 1, a2);
;             WAIT_V(8); WAIT_L(0); BAR; MMA(0, 0, At, B0); MMA(0, 1, At, B1); BAR; SCHED;
;             LDA(At, 1, 1); STG_B(1, 0, b3); STG_B(1, 1, b3); STG_A(1, 0, a3);
;             WAIT_V(8); WAIT_L(0); BAR; MMA(1, 0, At, B0); MMA(1, 1, At, B1); BAR; SCHED;
;         }
.Lkmid_1338:
	ds_read_b128 v[158:161], v156 offset:32768
	ds_read_b128 v[162:165], v156 offset:33792
	ds_read_b128 v[166:169], v156 offset:34816
	ds_read_b128 v[170:173], v156 offset:35840
	ds_read_b128 v[174:177], v156 offset:49152
	ds_read_b128 v[178:181], v156 offset:50176
	ds_read_b128 v[182:185], v156 offset:51200
	ds_read_b128 v[196:199], v156 offset:52224
	ds_read_b128 v[200:203], v157 offset:32768
	ds_read_b128 v[212:215], v157 offset:33792
	ds_read_b128 v[216:219], v157 offset:34816
	ds_read_b128 v[220:223], v157 offset:35840
	ds_read_b128 v[224:227], v157 offset:36864
	ds_read_b128 v[228:231], v157 offset:37888
	ds_read_b128 v[232:235], v157 offset:38912
	ds_read_b128 v[236:239], v157 offset:39936
	s_add_u32 s54, s54, 0x40000
	s_addc_u32 s55, s55, 0
	s_add_u32 m0, s100, 0x4000
	s_nop 0
	global_load_lds_dwordx4 v128, s[54:55]
	s_add_u32 m0, s100, 0x6000
	s_nop 0
	global_load_lds_dwordx4 v130, s[54:55]
	s_waitcnt vmcnt(8)
	s_waitcnt lgkmcnt(0)
	s_barrier
	s_waitcnt lgkmcnt(0)
	v_mfma_f32_16x16x32_bf16 v[124:127], v[158:161], v[200:203], v[124:127]
	v_mfma_f32_16x16x32_bf16 v[120:123], v[166:169], v[200:203], v[120:123]
	v_mfma_f32_16x16x32_bf16 v[104:107], v[158:161], v[216:219], v[104:107]
	v_mfma_f32_16x16x32_bf16 v[108:111], v[166:169], v[216:219], v[108:111]
	v_mfma_f32_16x16x32_bf16 v[92:95], v[158:161], v[224:227], v[92:95]
	v_mfma_f32_16x16x32_bf16 v[88:91], v[166:169], v[224:227], v[88:91]
	v_mfma_f32_16x16x32_bf16 v[72:75], v[158:161], v[232:235], v[72:75]
	v_mfma_f32_16x16x32_bf16 v[76:79], v[166:169], v[232:235], v[76:79]
	v_mfma_f32_16x16x32_bf16 v[124:127], v[162:165], v[212:215], v[124:127]
	v_mfma_f32_16x16x32_bf16 v[120:123], v[170:173], v[212:215], v[120:123]
	v_mfma_f32_16x16x32_bf16 v[104:107], v[162:165], v[220:223], v[104:107]
	v_mfma_f32_16x16x32_bf16 v[108:111], v[170:173], v[220:223], v[108:111]
	v_mfma_f32_16x16x32_bf16 v[92:95], v[162:165], v[228:231], v[92:95]
	v_mfma_f32_16x16x32_bf16 v[88:91], v[170:173], v[228:231], v[88:91]
	v_mfma_f32_16x16x32_bf16 v[72:75], v[162:165], v[236:239], v[72:75]
	v_mfma_f32_16x16x32_bf16 v[76:79], v[170:173], v[236:239], v[76:79]
	v_mfma_f32_16x16x32_bf16 v[116:119], v[174:177], v[200:203], v[116:119]
	v_mfma_f32_16x16x32_bf16 v[112:115], v[182:185], v[200:203], v[112:115]
	v_mfma_f32_16x16x32_bf16 v[96:99], v[174:177], v[216:219], v[96:99]
	v_mfma_f32_16x16x32_bf16 v[100:103], v[182:185], v[216:219], v[100:103]
	v_mfma_f32_16x16x32_bf16 v[84:87], v[174:177], v[224:227], v[84:87]
	v_mfma_f32_16x16x32_bf16 v[80:83], v[182:185], v[224:227], v[80:83]
	v_mfma_f32_16x16x32_bf16 v[64:67], v[174:177], v[232:235], v[64:67]
	v_mfma_f32_16x16x32_bf16 v[68:71], v[182:185], v[232:235], v[68:71]
	v_mfma_f32_16x16x32_bf16 v[116:119], v[178:181], v[212:215], v[116:119]
	v_mfma_f32_16x16x32_bf16 v[112:115], v[196:199], v[212:215], v[112:115]
	v_mfma_f32_16x16x32_bf16 v[96:99], v[178:181], v[220:223], v[96:99]
	v_mfma_f32_16x16x32_bf16 v[100:103], v[196:199], v[220:223], v[100:103]
	v_mfma_f32_16x16x32_bf16 v[84:87], v[178:181], v[228:231], v[84:87]
	v_mfma_f32_16x16x32_bf16 v[80:83], v[196:199], v[228:231], v[80:83]
	v_mfma_f32_16x16x32_bf16 v[64:67], v[178:181], v[236:239], v[64:67]
	v_mfma_f32_16x16x32_bf16 v[68:71], v[196:199], v[236:239], v[68:71]
	s_barrier
	ds_read_b128 v[200:203], v157 offset:49152
	ds_read_b128 v[212:215], v157 offset:50176
	ds_read_b128 v[216:219], v157 offset:51200
	ds_read_b128 v[220:223], v157 offset:52224
	ds_read_b128 v[224:227], v157 offset:53248
	ds_read_b128 v[228:231], v157 offset:54272
	ds_read_b128 v[232:235], v157 offset:55296
	ds_read_b128 v[236:239], v157 offset:56320
	s_add_u32 s8, s8, s2
	s_addc_u32 s9, s9, s3
	s_add_u32 m0, s100, 0x18000
	s_nop 0
	global_load_lds_dwordx4 v128, s[8:9]
	s_add_u32 m0, s100, 0x1a000
	s_nop 0
	global_load_lds_dwordx4 v130, s[8:9]
	s_add_u32 s8, s8, 0x40000
	s_addc_u32 s9, s9, 0
	s_add_u32 m0, s100, 0x1c000
	s_nop 0
	global_load_lds_dwordx4 v128, s[8:9]
	s_add_u32 m0, s100, 0x1e000
	s_nop 0
	global_load_lds_dwordx4 v130, s[8:9]
	s_sub_u32 s96, s54, 0x40000
	s_subb_u32 s97, s55, 0
	s_add_u32 s96, s96, s2
	s_addc_u32 s97, s97, s3
	s_add_u32 m0, s100, 0x8000
	s_nop 0
	global_load_lds_dwordx4 v128, s[96:97]
	s_add_u32 m0, s100, 0xa000
	s_nop 0
	global_load_lds_dwordx4 v130, s[96:97]
	s_waitcnt vmcnt(8)
	s_waitcnt lgkmcnt(0)
	s_barrier
	s_waitcnt lgkmcnt(0)
	v_mfma_f32_16x16x32_bf16 v[60:63], v[158:161], v[200:203], v[60:63]
	v_mfma_f32_16x16x32_bf16 v[56:59], v[166:169], v[200:203], v[56:59]
	v_mfma_f32_16x16x32_bf16 v[40:43], v[158:161], v[216:219], v[40:43]
	v_mfma_f32_16x16x32_bf16 v[44:47], v[166:169], v[216:219], v[44:47]
	v_mfma_f32_16x16x32_bf16 v[28:31], v[158:161], v[224:227], v[28:31]
	v_mfma_f32_16x16x32_bf16 v[24:27], v[166:169], v[224:227], v[24:27]
	v_mfma_f32_16x16x32_bf16 v[8:11], v[158:161], v[232:235], v[8:11]
	v_mfma_f32_16x16x32_bf16 v[12:15], v[166:169], v[232:235], v[12:15]
	v_mfma_f32_16x16x32_bf16 v[60:63], v[162:165], v[212:215], v[60:63]
	v_mfma_f32_16x16x32_bf16 v[56:59], v[170:173], v[212:215], v[56:59]
	v_mfma_f32_16x16x32_bf16 v[40:43], v[162:165], v[220:223], v[40:43]
	v_mfma_f32_16x16x32_bf16 v[44:47], v[170:173], v[220:223], v[44:47]
	v_mfma_f32_16x16x32_bf16 v[28:31], v[162:165], v[228:231], v[28:31]
	v_mfma_f32_16x16x32_bf16 v[24:27], v[170:173], v[228:231], v[24:27]
	v_mfma_f32_16x16x32_bf16 v[8:11], v[162:165], v[236:239], v[8:11]
	v_mfma_f32_16x16x32_bf16 v[12:15], v[170:173], v[236:239], v[12:15]
	v_mfma_f32_16x16x32_bf16 v[52:55], v[174:177], v[200:203], v[52:55]
	v_mfma_f32_16x16x32_bf16 v[48:51], v[182:185], v[200:203], v[48:51]
	v_mfma_f32_16x16x32_bf16 v[32:35], v[174:177], v[216:219], v[32:35]
	v_mfma_f32_16x16x32_bf16 v[36:39], v[182:185], v[216:219], v[36:39]
	v_mfma_f32_16x16x32_bf16 v[20:23], v[174:177], v[224:227], v[20:23]
	v_mfma_f32_16x16x32_bf16 v[16:19], v[182:185], v[224:227], v[16:19]
	v_mfma_f32_16x16x32_bf16 v[0:3], v[174:177], v[232:235], v[0:3]
	v_mfma_f32_16x16x32_bf16 v[4:7], v[182:185], v[232:235], v[4:7]
	v_mfma_f32_16x16x32_bf16 v[52:55], v[178:181], v[212:215], v[52:55]
	v_mfma_f32_16x16x32_bf16 v[48:51], v[196:199], v[212:215], v[48:51]
	v_mfma_f32_16x16x32_bf16 v[32:35], v[178:181], v[220:223], v[32:35]
	v_mfma_f32_16x16x32_bf16 v[36:39], v[196:199], v[220:223], v[36:39]
	v_mfma_f32_16x16x32_bf16 v[20:23], v[178:181], v[228:231], v[20:23]
	v_mfma_f32_16x16x32_bf16 v[16:19], v[196:199], v[228:231], v[16:19]
	v_mfma_f32_16x16x32_bf16 v[0:3], v[178:181], v[236:239], v[0:3]
	v_mfma_f32_16x16x32_bf16 v[4:7], v[196:199], v[236:239], v[4:7]
	s_barrier
	s_add_i32 s94, s94, 2
	s_add_u32 s36, s36, 0x100
	s_addc_u32 s37, s37, 0
	s_cmp_gt_u32 s94, 13
	s_cbranch_scc0 .LBB0_1338
	s_setprio 0
	s_and_saveexec_b64 s[8:9], s[44:45]
	s_cbranch_execz .LBB0_1341
	s_barrier

; template <int BMODE, class Epi, class TileFn>
; DEV void gemm_loop(LAS unsigned char* lds, const bf16_t* __restrict__ A, int lda, const bf16_t* __restrict__ B, int ldb, int K, const Epi& epi, int t0, int tstep, int tend, const TileFn& tf) {
;     ...
;         int nrow = brow, ncol = bcol;
;         if (has_next) tf(tt + tstep, nrow, ncol);
;         const char* nA = (const char*)(A + (size_t)nrow * lda);
;         const char* nB = BMODE == 0 ? (const char*)(B + (size_t)ncol * ldb) : (const char*)(B + (size_t)ncol * 8);
;         for (int t = 0; t < nt; t += 2) {
.LBB0_1440:
	s_mul_i32 s46, s7, 0x1600
	s_mul_hi_i32 s47, s7, 0x1600
	s_add_u32 s30, s70, s46
	s_addc_u32 s37, s71, s47
	s_mul_i32 s48, s28, 0x1600
	s_mul_hi_i32 s49, s28, 0x1600
	s_add_u32 s50, s42, s48
	s_addc_u32 s54, s43, s49
	s_add_u32 s55, s66, s8
	s_addc_u32 s74, s67, s9
	v_lshl_add_u64 v[120:121], v[200:201], 0, s[8:9]
	v_lshl_add_u64 v[122:123], v[202:203], 0, s[8:9]
	v_readlane_b32 s8, v250, 4
	s_add_u32 s75, s8, s0
	v_readlane_b32 s0, v250, 5
	s_addc_u32 s76, s0, s1
	s_mov_b32 s77, -2
	s_mov_b64 s[0:1], 0
	v_readfirstlane_b32 s101, v188
	s_nop 3
	s_cmp_lt_u32 s101, 0x100
	s_cbranch_scc1 .Lsp_1441
	s_setprio 1
